# PH4 workers: last-round pool tiles moved to blocks without a fifth attention item (with coalesced-wait scan)
# baseline (speedup 1.0000x reference)
.LBB0_770:
	v_readlane_b32 s0, v207, 3
	s_add_i32 s9, s9, s0
	s_cmpk_lg_i32 s0, 0x100
	s_cbranch_scc1 .Lwbal_go
	s_cmpk_ge_i32 s9, 0x600
	s_cbranch_scc1 .LBB0_1028
	s_cmpk_lt_i32 s9, 0x500
	s_cbranch_scc1 .Lwbal_go
	s_sub_i32 s9, 0xaff, s9
.Lwbal_go:
	s_mov_b32 s8, s9
	v_readlane_b32 s0, v207, 2
	s_cmp_lt_i32 s9, s0
	s_cbranch_scc0 .LBB0_1028
